# deferred conv-tile boundary fix-up moved from workgroups 192..255 (longest path) to workgroups 0..63 (same XCD, same pm, have slack)
# baseline (speedup 1.0000x reference)
; __device__ __forceinline__ unsigned xb_ld(unsigned* p)              { return __hip_atomic_load(p, __ATOMIC_RELAXED, __HIP_MEMORY_SCOPE_AGENT); }
; __device__ __forceinline__ void group_wait(unsigned* cnt, unsigned want, unsigned* bar) {
;     if (threadIdx.x == 0) {
;         unsigned sp = 0;
;         while (__hip_atomic_load(cnt, __ATOMIC_RELAXED, __HIP_MEMORY_SCOPE_AGENT) < want) {
;             __builtin_amdgcn_s_sleep(2);
;             if ((++sp & 255u) == 0u) { if (xb_ld(&bar[XB_TMO])) break; if (sp > XB_SPIN_CAP) { atomicAdd(&bar[XB_TMO], 1u); break; } }
;         }
; __global__ void __launch_bounds__(NWAVES * 64, 2) fwd_megakernel(Args a) {
;     ...
;             if (l >= 24) {
;                 group_wait(gcc, 32u, (unsigned*)(ws + WS_BAR));
.LBB0_313:
	s_or_b64 exec, exec, s[0:1]
	s_cmpk_gt_u32 s98, 0x3f
	s_barrier
	s_cbranch_scc1 .LBB0_339
	s_mov_b64 s[0:1], exec
	v_readlane_b32 s2, v253, 23
	v_readlane_b32 s3, v253, 24
	s_and_b64 s[2:3], s[0:1], s[2:3]
	s_mov_b64 exec, s[2:3]
	s_cbranch_execz .LBB0_329
	v_mov_b32_e32 v0, 0
	global_load_dword v1, v0, s[8:9] sc1
	s_waitcnt vmcnt(0)
	v_cmp_lt_u32_e32 vcc, 31, v1
	s_cbranch_vccnz .LBB0_328
	s_add_u32 s2, s96, 0x180200
	s_addc_u32 s3, s97, 0
	s_mov_b32 s12, 1
	s_branch .LBB0_318

; __device__ __forceinline__ void conv_fixup(int idx, int lane, const float* DEF, const float* HALO, const float* conv_w, const float* gain_c, bf16* MIX, float* SSC) {
;     const int pm = idx >> 1, rho = idx & 1;
;     if ((pm & 7) == 0) return;
;     const int c = lane * 16, t = pm * 256 + rho;
;     const float* d = DEF + ((size_t)(pm * 2 + rho) * 3) * 1024 + c;
;     const float* p1 = rho ? (DEF + ((size_t)(pm * 2) * 3 + 1) * 1024 + c) : (HALO + ((size_t)(pm - 1) * 2 + 1) * 1024 + c);
;     const float* p2 = rho ? (HALO + ((size_t)(pm - 1) * 2 + 1) * 1024 + c) : (HALO + ((size_t)(pm - 1) * 2) * 1024 + c);
; __global__ void __launch_bounds__(NWAVES * 64, 2) fwd_megakernel(Args a) {
;     ...
;             if (l >= 24) {
;                 group_wait(gcc, 32u, (unsigned*)(ws + WS_BAR));
;                 if (l != 24 && wave < 2) conv_fixup(2 * (gb * 8 + (l - 24)) + wave, lane, DEF, HALO, a.conv_w, a.norm_conv, MIX, SSC);
.LBB0_329:
	s_or_b64 exec, exec, s[0:1]
	s_cmp_lg_u32 s90, 0
	v_readlane_b32 s2, v253, 33
	s_cselect_b64 s[0:1], -1, 0
	s_cmpk_lt_u32 s2, 0x80
	s_cselect_b64 s[2:3], -1, 0
	s_and_b64 s[0:1], s[0:1], s[2:3]
	s_andn2_b64 vcc, exec, s[0:1]
	s_barrier
	s_cbranch_vccnz .LBB0_339
	s_and_b32 s0, s98, 56
	s_cmp_eq_u32 s0, 0
	s_cbranch_scc1 .LBB0_339
	s_lshl_b32 s0, s33, 4
	s_lshl_b32 s1, s90, 1
	s_add_i32 s1, s1, s0
	s_mov_b32 s4, s1
	s_ashr_i32 s0, s4, 1
	v_readlane_b32 s1, v253, 33
	s_cmp_lt_u32 s1, 64
	s_cbranch_scc1 .LBB0_333
	s_mul_i32 s2, s4, 0x3000
	v_readlane_b32 s6, v253, 44
	s_mul_hi_i32 s1, s4, 0x3000
	v_readlane_b32 s7, v253, 45
	s_add_u32 s12, s6, s2
	s_addc_u32 s13, s7, s1
	s_ashr_i32 s1, s0, 31
	s_lshl_b64 s[2:3], s[0:1], 13
	s_add_u32 s6, s2, 0xffffe000
	s_addc_u32 s7, s3, -1
	s_mov_b64 s[2:3], 0
	s_branch .LBB0_334
